# GEMM phase prologue: the second K-tile's staging loads are issued before the first landing wait (vmcnt 2 -> 8 after all 14 loads)
# baseline (speedup 1.0000x reference)
.LBB0_90:
	s_add_i32 m0, s75, 0x18000
	v_lshl_add_u64 v[10:11], v[10:11], 0, s[56:57]
	global_load_lds_dwordx4 v[10:11], off
	v_lshl_add_u64 v[6:7], v[6:7], 0, s[56:57]
	s_add_i32 m0, s75, 0x1a000
	s_add_i32 s26, s75, 0x8000
	global_load_lds_dwordx4 v[6:7], off
	v_lshl_add_u64 v[6:7], v[8:9], 0, s[56:57]
	s_mov_b32 m0, s26
	s_add_i32 s27, s75, 0xa000
	global_load_lds_dwordx4 v[6:7], off
	v_lshl_add_u64 v[6:7], v[12:13], 0, s[56:57]
	s_mov_b32 m0, s27
	v_lshl_add_u64 v[4:5], v[4:5], 0, s[56:57]
	global_load_lds_dwordx4 v[6:7], off
	s_add_i32 m0, s75, 0x1c000
	v_lshl_add_u64 v[2:3], v[2:3], 0, s[56:57]
	global_load_lds_dwordx4 v[4:5], off
	s_add_i32 m0, s75, 0x1e000
	s_lshr_b32 s34, s6, 6
	global_load_lds_dwordx4 v[2:3], off
	s_waitcnt vmcnt(8)
	s_barrier
	v_and_b32_e32 v2, 15, v0
	v_and_b32_e32 v3, 48, v0
	v_lshlrev_b32_e32 v2, 6, v2
	v_lshlrev_b32_e32 v0, 2, v0
	v_or_b32_e32 v4, v2, v3
	s_lshl_b32 s6, s10, 13
	v_and_b32_e32 v0, 32, v0
	v_bitop3_b32 v2, v2, v0, v3 bitop3:0x36
	v_bitop3_b32 v3, v4, s6, v0 bitop3:0xde
	s_lshl_b32 s6, s28, 12
	s_and_b32 s6, s6, 0x3000
	s_add_i32 s82, s34, -2
	s_cmpk_lt_u32 s9, 0x100
	s_cselect_b64 s[28:29], -1, 0
	s_lshr_b32 s83, s8, 5
	v_cvt_f32_u32_e32 v0, s83
	v_or_b32_e32 v190, s6, v2
	s_lshr_b32 s6, s8, 8
	v_readlane_b32 s7, v240, 39
	v_rcp_iflag_f32_e32 v0, v0
	s_mul_i32 s80, s6, s7
	s_lshr_b32 s6, s80, 3
	s_cmp_lg_u64 s[86:87], 0
	v_mul_f32_e32 v0, 0x4f7ffffe, v0
	v_cvt_u32_f32_e32 v0, v0
	v_writelane_b32 v240, s6, 45
	s_cselect_b64 s[30:31], -1, 0
	s_sub_i32 s6, 0, s83
	v_readfirstlane_b32 s7, v0
	v_add_u32_e32 v0, v16, v14
	v_add_lshl_u32 v0, v0, v15, 1
	s_waitcnt vmcnt(6)
	s_mul_i32 s6, s6, s7
	v_lshl_add_u64 v[158:159], s[18:19], 0, v[0:1]
	v_add_u32_e32 v0, v19, v17
	s_mul_hi_u32 s6, s7, s6
	v_add_lshl_u32 v0, v0, v18, 1
	s_mov_b32 s33, 0
	s_add_i32 s6, s7, s6
	v_lshl_add_u64 v[160:161], s[18:19], 0, v[0:1]
	v_add_u32_e32 v191, 0, v3
	s_barrier
	v_writelane_b32 v240, s6, 46
	s_branch .LBB0_93
